# P4: 11 of the epilogue's first-chunk HB/PP operand loads issued before the K-loop into VGPRs idle during the K-loop
# baseline (speedup 1.0000x reference)
; __device__ __forceinline__ float bflo(unsigned u) { return __uint_as_float(u << 16); }
; __device__ __forceinline__ float bfhi(unsigned u) { return __uint_as_float(u & 0xffff0000u); }
; #define PG8_STAGE(bufoff, gbase, voff) do { unsigned long long _gb = (unsigned long long)(gbase); asm volatile("" : "+s"(_gb)); _Pragma("unroll") for (int _i = 0; _i < 2; ++_i) \
;         __builtin_amdgcn_global_load_lds((const GAS unsigned*)((const GAS char*)_gb + (voff)[_i]), (LAS unsigned*)(lds + (bufoff) + ldsw + _i * 8192), 16, 0, 0); } while (0)
; #define PG8_WAIT_V(n) asm volatile("s_waitcnt vmcnt(" #n ")" ::: "memory")
; #define PG8_BAR __builtin_amdgcn_s_barrier()
; template <class Epi, bool ALIGN_EPI>
; __device__ __forceinline__ void gemm_phase(LAS unsigned char* lds, const Gemm g, const StaticOrder& S, const Epi& E, const int wid) {
;     ...
;     PG8_STAGE(PG8_SB(0, 0), cB, voffB); PG8_STAGE(PG8_SB(0, 1), cB + hstepB, voffB); PG8_STAGE(PG8_SA(0, 0), cA, voffA); PG8_STAGE(PG8_SA(0, 1), cA + hstep, voffA);
;     if (wr == 1) PG8_BAR;
;     PG8_WAIT_V(2); PG8_BAR;
;     PG8_STAGE(PG8_SB(1, 0), cB + kstep, voffB); PG8_STAGE(PG8_SA(1, 0), cA + kstep, voffA); PG8_STAGE(PG8_SB(1, 1), cB + hstepB + kstep, voffB);
;     PG8_WAIT_V(6); PG8_BAR;
;     __device__ __forceinline__ void operator()(const Acc& acc, const Unit& u, int wr, int wc, int fr, int fq) const {
;     ...
;             for (int m = 0; m < 4; ++m) { const int row = u.pm * 256 + ai * 128 + wr * 64 + m * 16 + fr; const size_t off = (size_t)row * DM + colbase;
;                 rsv[m] = rowss[row];
; #pragma unroll
;                 for (int bj = 0; bj < 2; ++bj) { const u32x4 hw = __builtin_nontemporal_load((const u32x4*)(hin + off + 32 * bj));
;                     hv[m][bj][0] = (f32x4){bflo(hw.x), bfhi(hw.x), bflo(hw.y), bfhi(hw.y)}; hv[m][bj][1] = (f32x4){bflo(hw.z), bfhi(hw.z), bflo(hw.w), bfhi(hw.w)};
;                     pw[m][bj] = __builtin_nontemporal_load((const u32x4*)(PP + off + 32 * bj)); } }
.LBB0_801:
	s_and_b32 s42, 0xffff, s4
	s_add_u32 s8, s80, 0xc300000
	s_addc_u32 s9, s81, 0
	s_add_u32 s4, s18, 0x80
	s_addc_u32 s5, s19, 0
	s_waitcnt vmcnt(2)
	v_readfirstlane_b32 s3, v251
	v_readfirstlane_b32 s2, v250
	s_barrier
	s_add_i32 m0, s28, 0x18000
	v_lshl_add_u64 v[2:3], s[4:5], 0, v[180:181]
	global_load_lds_dwordx4 v[2:3], off
	s_add_i32 m0, s28, 0x1a000
	v_lshl_add_u64 v[2:3], s[4:5], 0, v[176:177]
	s_add_u32 s4, s20, 0x80
	s_addc_u32 s5, s21, 0
	s_add_i32 s34, s28, 0x8000
	global_load_lds_dwordx4 v[2:3], off
	s_mov_b32 m0, s34
	v_lshl_add_u64 v[2:3], s[4:5], 0, v[182:183]
	s_add_i32 s35, s28, 0xa000
	global_load_lds_dwordx4 v[2:3], off
	v_lshl_add_u64 v[2:3], s[4:5], 0, v[178:179]
	s_add_u32 s4, s18, 0x20080
	s_mov_b32 m0, s35
	s_addc_u32 s5, s19, 0
	global_load_lds_dwordx4 v[2:3], off
	s_add_i32 m0, s28, 0x1c000
	v_lshl_add_u64 v[2:3], s[4:5], 0, v[180:181]
	global_load_lds_dwordx4 v[2:3], off
	v_lshl_add_u64 v[2:3], s[4:5], 0, v[176:177]
	s_add_i32 m0, s28, 0x1e000
	v_and_b32_e32 v5, 48, v0
	global_load_lds_dwordx4 v[2:3], off
	v_and_b32_e32 v2, 15, v0
	v_or_b32_e32 v3, s79, v2
	v_lshlrev_b32_e32 v4, 6, v3
	s_movk_i32 s4, 0x3c0
	v_and_b32_e32 v1, 0xfffffc00, v1
	v_lshlrev_b32_e32 v3, 2, v3
	v_lshlrev_b32_e32 v0, 2, v0
	v_and_or_b32 v4, v4, s4, v5
	v_add_u32_e32 v6, s94, v1
	v_and_b32_e32 v3, 32, v3
	v_lshl_or_b32 v2, v2, 6, v5
	v_add_u32_e32 v1, s93, v1
	v_and_b32_e32 v0, 32, v0
	s_waitcnt vmcnt(6)
	v_and_b32_e32 v252, 15, v200
	v_bfe_u32 v253, v200, 4, 2
	s_lshl_b32 s38, s42, 8
	s_or_b32 s38, s38, s86
	s_lshl_b32 s39, s41, 8
	s_add_i32 s39, s39, s79
	v_lshl_add_u32 v253, v253, 3, s38
	v_add_u32_e32 v252, s39, v252
	v_lshl_add_u32 v252, v252, 11, v253
	v_lshlrev_b32_e32 v252, 1, v252
	v_add_u32_e32 v251, 0x10000, v252
	v_add_u32_e32 v250, 0x20000, v252
	global_load_dwordx4 v[222:225], v252, s[6:7] nt
	global_load_dwordx4 v[210:213], v252, s[8:9] nt
	global_load_dwordx4 v[214:217], v252, s[6:7] offset:64 nt
	global_load_dwordx4 v[218:221], v252, s[8:9] offset:64 nt
	global_load_dwordx4 v[226:229], v251, s[6:7] nt
	global_load_dwordx4 v[230:233], v251, s[6:7] offset:64 nt
	global_load_dwordx4 v[234:237], v251, s[8:9] nt
	global_load_dwordx4 v[238:241], v251, s[8:9] offset:64 nt
	global_load_dwordx4 v[242:245], v250, s[6:7] nt
	global_load_dwordx4 v[246:249], v250, s[6:7] offset:64 nt
	global_load_dwordx4 v[250:253], v250, s[8:9] nt
	v_bitop3_b32 v3, v4, v6, v3 bitop3:0xde
	v_bitop3_b32 v201, v2, v1, v0 bitop3:0xde
	s_add_i32 s38, 0, 0x10000
	s_add_i32 s39, 0, 0x14000
	s_mov_b32 s36, 0
	s_ashr_i32 s37, s78, 31
	v_mov_b64_e32 v[184:185], 0x100
	v_mov_b64_e32 v[186:187], 0xff
	v_add_u32_e32 v202, s38, v201
	v_add_u32_e32 v203, s39, v201
	v_add_u32_e32 v204, 0, v3
	v_mov_b32_e32 v205, 0x358637bd
	s_mov_b32 s40, 0x800000
	s_barrier
	s_branch .LBB0_804

; __device__ __forceinline__ float bflo(unsigned u) { return __uint_as_float(u << 16); }
;     __device__ __forceinline__ void operator()(const Acc& acc, const Unit& u, int wr, int wc, int fr, int fq) const {
;     ...
;             for (int m = 0; m < 4; ++m) { const int row = u.pm * 256 + ai * 128 + wr * 64 + m * 16 + fr; const size_t off = (size_t)row * DM + colbase;
;                 rsv[m] = rowss[row];
; #pragma unroll
;                 for (int bj = 0; bj < 2; ++bj) { const u32x4 hw = __builtin_nontemporal_load((const u32x4*)(hin + off + 32 * bj));
;                     hv[m][bj][0] = (f32x4){bflo(hw.x), bfhi(hw.x), bflo(hw.y), bfhi(hw.y)}; hv[m][bj][1] = (f32x4){bflo(hw.z), bfhi(hw.z), bflo(hw.w), bfhi(hw.w)};
;                     pw[m][bj] = __builtin_nontemporal_load((const u32x4*)(PP + off + 32 * bj)); } }
; #pragma unroll
;             for (int m = 0; m < 4; ++m) {
;                 const int row = u.pm * 256 + ai * 128 + wr * 64 + m * 16 + fr;
;                 const float rs = rsqrtf(rsv[m] * (1.0f / DM) + EPS) * -1.4426950408889634f;
; #pragma unroll
;                 for (int bj = 0; bj < 2; ++bj) {
;                     const size_t off = (size_t)row * DM + colbase + 32 * bj;
;                     f32x4 h0 = hv[m][bj][0], h1 = hv[m][bj][1];
;                     const u32x4 p4 = pw[m][bj];
;                     const f32x4 a0 = acc[ai][bj][m][0], a1 = acc[ai][bj][m][1];
;                     h0.x += bflo(p4.x) * __builtin_amdgcn_rcpf(1.0f + __builtin_amdgcn_exp2f(a0.x * rs));
;                     h0.y += bfhi(p4.x) * __builtin_amdgcn_rcpf(1.0f + __builtin_amdgcn_exp2f(a0.y * rs));
;                     h0.z += bflo(p4.y) * __builtin_amdgcn_rcpf(1.0f + __builtin_amdgcn_exp2f(a0.z * rs));
;                     h0.w += bfhi(p4.y) * __builtin_amdgcn_rcpf(1.0f + __builtin_amdgcn_exp2f(a0.w * rs));
;                     h1.x += bflo(p4.z) * __builtin_amdgcn_rcpf(1.0f + __builtin_amdgcn_exp2f(a1.x * rs));
;                     h1.y += bfhi(p4.z) * __builtin_amdgcn_rcpf(1.0f + __builtin_amdgcn_exp2f(a1.y * rs));
;                     h1.z += bflo(p4.w) * __builtin_amdgcn_rcpf(1.0f + __builtin_amdgcn_exp2f(a1.z * rs));
;                     h1.w += bfhi(p4.w) * __builtin_amdgcn_rcpf(1.0f + __builtin_amdgcn_exp2f(a1.w * rs));
;                     *(f32x4*)(out + off) = h0; *(f32x4*)(out + off + 4) = h1;
.LBB0_814:
	s_waitcnt vmcnt(0)
	v_mov_b64_e32 v[206:207], v[222:223]
	v_mov_b64_e32 v[208:209], v[224:225]
	v_mov_b64_e32 v[172:173], v[226:227]
	v_mov_b64_e32 v[174:175], v[228:229]
	v_mov_b64_e32 v[164:165], v[230:231]
	v_mov_b64_e32 v[166:167], v[232:233]
	v_mov_b64_e32 v[168:169], v[234:235]
	v_mov_b64_e32 v[170:171], v[236:237]
	v_mov_b64_e32 v[160:161], v[238:239]
	v_mov_b64_e32 v[162:163], v[240:241]
	v_mov_b64_e32 v[156:157], v[242:243]
	v_mov_b64_e32 v[158:159], v[244:245]
	v_mov_b64_e32 v[148:149], v[246:247]
	v_mov_b64_e32 v[150:151], v[248:249]
	v_mov_b64_e32 v[152:153], v[250:251]
	v_mov_b64_e32 v[154:155], v[252:253]
	v_mov_b32_e32 v128, v200
	s_lshl_b32 s11, s42, 8
	v_and_b32_e32 v129, 15, v128
	v_bfe_u32 v128, v128, 4, 2
	s_or_b32 s11, s11, s86
	s_nop 0
	v_lshl_add_u32 v188, v128, 3, s11
	s_lshl_b32 s11, s41, 8
	s_add_i32 s11, s11, s79
	v_add_u32_e32 v190, s11, v129
	v_ashrrev_i32_e32 v191, 31, v190
	v_lshl_add_u64 v[192:193], v[190:191], 2, s[80:81]
	flat_load_dword v226, v[192:193]
	v_ashrrev_i32_e32 v189, 31, v188
	v_lshlrev_b64 v[128:129], 11, v[190:191]
	v_lshl_add_u64 v[222:223], v[128:129], 0, v[188:189]
	v_lshlrev_b64 v[128:129], 1, v[222:223]
	v_lshl_add_u64 v[130:131], s[6:7], 0, v[128:129]
	v_lshl_add_u64 v[128:129], s[8:9], 0, v[128:129]
	flat_load_dword v234, v[192:193] offset:64
	flat_load_dword v235, v[192:193] offset:128
	flat_load_dword v191, v[192:193] offset:192
	v_add_u32_e32 v132, 16, v190
	v_add_u32_e32 v134, 32, v190
	v_add_u32_e32 v136, 48, v190
	v_ashrrev_i32_e32 v133, 31, v132
	v_ashrrev_i32_e32 v135, 31, v134
	v_ashrrev_i32_e32 v137, 31, v136
	v_lshlrev_b64 v[132:133], 11, v[132:133]
	v_lshlrev_b64 v[134:135], 11, v[134:135]
	v_lshlrev_b64 v[136:137], 11, v[136:137]
	v_lshl_add_u64 v[198:199], v[132:133], 0, v[188:189]
	v_lshl_add_u64 v[196:197], v[134:135], 0, v[188:189]
	v_lshl_add_u64 v[194:195], v[136:137], 0, v[188:189]
	v_lshlrev_b64 v[132:133], 1, v[198:199]
	v_lshlrev_b64 v[134:135], 1, v[196:197]
	v_lshlrev_b64 v[136:137], 1, v[194:195]
	v_lshl_add_u64 v[128:129], s[6:7], 0, v[132:133]
	v_lshl_add_u64 v[130:131], s[8:9], 0, v[132:133]
	v_lshl_add_u64 v[132:133], s[6:7], 0, v[134:135]
	v_lshl_add_u64 v[134:135], s[8:9], 0, v[134:135]
	v_lshl_add_u64 v[138:139], s[6:7], 0, v[136:137]
	v_lshl_add_u64 v[224:225], s[8:9], 0, v[136:137]
	flat_load_dwordx4 v[144:147], v[134:135] offset:64 nt
	flat_load_dwordx4 v[140:143], v[138:139] nt
	s_nop 0
	flat_load_dwordx4 v[132:135], v[138:139] offset:64 nt
	s_nop 0
	flat_load_dwordx4 v[136:139], v[224:225] nt
	flat_load_dwordx4 v[128:131], v[224:225] offset:64 nt
	s_waitcnt vmcnt(0) lgkmcnt(0)
	v_fmamk_f32 v224, v226, 0x3a000000, v205
	v_mul_f32_e32 v225, 0x4b800000, v224
	v_cmp_gt_f32_e32 vcc, s40, v224
	v_lshlrev_b32_e32 v228, 16, v208
	s_nop 0
	v_cndmask_b32_e32 v224, v224, v225, vcc
	v_rsq_f32_e32 v232, v224
	v_and_b32_e32 v229, 0xffff0000, v208
	v_lshlrev_b32_e32 v230, 16, v212
	v_and_b32_e32 v231, 0xffff0000, v212
	v_mul_f32_e32 v208, 0x45800000, v232
	v_cndmask_b32_e32 v208, v232, v208, vcc
	v_mul_f32_e32 v212, 0xbfb8aa3b, v208
	v_mul_f32_e32 v124, v124, v212
	v_mul_f32_e32 v125, v125, v212
	v_mul_f32_e32 v120, v120, v212
	v_mul_f32_e32 v121, v121, v212
	v_exp_f32_e32 v124, v124
	v_exp_f32_e32 v125, v125
	v_exp_f32_e32 v120, v120
	v_exp_f32_e32 v121, v121
	v_add_f32_e32 v124, 1.0, v124
	v_add_f32_e32 v125, 1.0, v125
	v_add_f32_e32 v208, 1.0, v120
	v_add_f32_e32 v233, 1.0, v121
	v_rcp_f32_e32 v120, v124
	v_rcp_f32_e32 v121, v125
	v_lshlrev_b32_e32 v224, 16, v206
	v_and_b32_e32 v225, 0xffff0000, v206
	v_lshlrev_b32_e32 v226, 16, v210
	v_and_b32_e32 v227, 0xffff0000, v210
	v_mul_f32_e32 v126, v126, v212
	v_mul_f32_e32 v127, v127, v212
	v_mul_f32_e32 v122, v122, v212
	v_exp_f32_e32 v126, v126
	v_exp_f32_e32 v127, v127
	v_pk_fma_f32 v[124:125], v[120:121], v[226:227], v[224:225]
	v_mul_f32_e32 v120, v123, v212
	v_exp_f32_e32 v122, v122
	v_exp_f32_e32 v123, v120
	v_mul_f32_e32 v116, v116, v212
	v_mul_f32_e32 v117, v117, v212
	v_exp_f32_e32 v116, v116
	v_exp_f32_e32 v117, v117
	v_mul_f32_e32 v118, v118, v212
	v_mul_f32_e32 v119, v119, v212
	v_add_f32_e32 v126, 1.0, v126
	v_add_f32_e32 v127, 1.0, v127
	v_exp_f32_e32 v118, v118
	v_exp_f32_e32 v119, v119
	v_mul_f32_e32 v112, v112, v212
	v_mul_f32_e32 v113, v113, v212
	v_rcp_f32_e32 v126, v126
	v_rcp_f32_e32 v127, v127
	v_add_f32_e32 v122, 1.0, v122
	v_add_f32_e32 v123, 1.0, v123
	v_exp_f32_e32 v112, v112
	v_exp_f32_e32 v113, v113
	v_rcp_f32_e32 v232, v208
	v_rcp_f32_e32 v233, v233
	v_rcp_f32_e32 v122, v122
	v_rcp_f32_e32 v123, v123
	v_add_f32_e32 v116, 1.0, v116
	v_add_f32_e32 v117, 1.0, v117
	v_lshlrev_b32_e32 v206, 16, v207
	v_and_b32_e32 v207, 0xffff0000, v207
	v_lshlrev_b32_e32 v210, 16, v211
	v_and_b32_e32 v211, 0xffff0000, v211
	v_rcp_f32_e32 v116, v116
	v_rcp_f32_e32 v117, v117
	v_add_f32_e32 v118, 1.0, v118
	v_add_f32_e32 v119, 1.0, v119
	v_pk_fma_f32 v[126:127], v[126:127], v[210:211], v[206:207]
	v_lshlrev_b32_e32 v206, 16, v209
	v_and_b32_e32 v207, 0xffff0000, v209
	v_lshlrev_b32_e32 v208, 16, v213
	v_and_b32_e32 v209, 0xffff0000, v213
	v_rcp_f32_e32 v118, v118
	v_rcp_f32_e32 v119, v119
	v_add_f32_e32 v112, 1.0, v112
	v_add_f32_e32 v113, 1.0, v113
	v_pk_fma_f32 v[120:121], v[232:233], v[230:231], v[228:229]
	v_pk_fma_f32 v[122:123], v[122:123], v[208:209], v[206:207]
	v_lshl_add_u64 v[206:207], v[222:223], 2, s[2:3]
	v_rcp_f32_e32 v112, v112
	v_rcp_f32_e32 v113, v113
	flat_store_dwordx4 v[206:207], v[120:123] offset:16
	flat_store_dwordx4 v[206:207], v[124:127]
	v_mul_f32_e32 v114, v114, v212
	v_lshlrev_b32_e32 v120, 16, v214
	v_and_b32_e32 v121, 0xffff0000, v214
	v_lshlrev_b32_e32 v122, 16, v218
; __device__ __forceinline__ float bflo(unsigned u) { return __uint_as_float(u << 16); }
; __device__ __forceinline__ float bfhi(unsigned u) { return __uint_as_float(u & 0xffff0000u); }
;     __device__ __forceinline__ void operator()(const Acc& acc, const Unit& u, int wr, int wc, int fr, int fq) const {
;     ...
;             for (int m = 0; m < 4; ++m) {
;                 const int row = u.pm * 256 + ai * 128 + wr * 64 + m * 16 + fr;
;                 const float rs = rsqrtf(rsv[m] * (1.0f / DM) + EPS) * -1.4426950408889634f;
; #pragma unroll
;                 for (int bj = 0; bj < 2; ++bj) {
;                     const size_t off = (size_t)row * DM + colbase + 32 * bj;
;                     f32x4 h0 = hv[m][bj][0], h1 = hv[m][bj][1];
;                     const u32x4 p4 = pw[m][bj];
;                     const f32x4 a0 = acc[ai][bj][m][0], a1 = acc[ai][bj][m][1];
;                     h0.x += bflo(p4.x) * __builtin_amdgcn_rcpf(1.0f + __builtin_amdgcn_exp2f(a0.x * rs));
;                     h0.y += bfhi(p4.x) * __builtin_amdgcn_rcpf(1.0f + __builtin_amdgcn_exp2f(a0.y * rs));
;                     h0.z += bflo(p4.y) * __builtin_amdgcn_rcpf(1.0f + __builtin_amdgcn_exp2f(a0.z * rs));
;                     h0.w += bfhi(p4.y) * __builtin_amdgcn_rcpf(1.0f + __builtin_amdgcn_exp2f(a0.w * rs));
;                     h1.x += bflo(p4.z) * __builtin_amdgcn_rcpf(1.0f + __builtin_amdgcn_exp2f(a1.x * rs));
;                     h1.y += bfhi(p4.z) * __builtin_amdgcn_rcpf(1.0f + __builtin_amdgcn_exp2f(a1.y * rs));
;                     h1.z += bflo(p4.w) * __builtin_amdgcn_rcpf(1.0f + __builtin_amdgcn_exp2f(a1.z * rs));
;                     h1.w += bfhi(p4.w) * __builtin_amdgcn_rcpf(1.0f + __builtin_amdgcn_exp2f(a1.w * rs));
;                     *(f32x4*)(out + off) = h0; *(f32x4*)(out + off + 4) = h1;
	v_and_b32_e32 v123, 0xffff0000, v218
	v_pk_fma_f32 v[116:117], v[116:117], v[122:123], v[120:121]
	v_lshlrev_b32_e32 v120, 16, v215
	v_and_b32_e32 v121, 0xffff0000, v215
	v_lshlrev_b32_e32 v122, 16, v219
	v_and_b32_e32 v123, 0xffff0000, v219
	v_pk_fma_f32 v[118:119], v[118:119], v[122:123], v[120:121]
	v_lshlrev_b32_e32 v120, 16, v216
	v_and_b32_e32 v121, 0xffff0000, v216
	v_lshlrev_b32_e32 v122, 16, v220
	v_and_b32_e32 v123, 0xffff0000, v220
	v_pk_fma_f32 v[112:113], v[112:113], v[122:123], v[120:121]
	v_fmamk_f32 v123, v234, 0x3a000000, v205
	v_mul_f32_e32 v124, 0x4b800000, v123
	v_cmp_gt_f32_e32 vcc, s40, v123
	flat_store_dwordx4 v[206:207], v[116:119] offset:128
	v_mul_f32_e32 v115, v115, v212
	v_cndmask_b32_e32 v123, v123, v124, vcc
	v_rsq_f32_e32 v124, v123
	v_exp_f32_e32 v114, v114
	v_exp_f32_e32 v115, v115
	v_lshlrev_b32_e32 v120, 16, v217
	v_mul_f32_e32 v116, 0x45800000, v124
	v_cndmask_b32_e32 v116, v124, v116, vcc
	v_mul_f32_e32 v116, 0xbfb8aa3b, v116
	v_mul_f32_e32 v108, v108, v116
	v_mul_f32_e32 v109, v109, v116
	v_exp_f32_e32 v108, v108
	v_exp_f32_e32 v109, v109
	v_mul_f32_e32 v110, v110, v116
	v_mul_f32_e32 v111, v111, v116
	v_exp_f32_e32 v110, v110
	v_exp_f32_e32 v111, v111
	v_mul_f32_e32 v104, v104, v116
	v_mul_f32_e32 v105, v105, v116
	v_add_f32_e32 v114, 1.0, v114
	v_add_f32_e32 v115, 1.0, v115
	v_exp_f32_e32 v104, v104
	v_exp_f32_e32 v105, v105
	v_mul_f32_e32 v106, v106, v116
	v_mul_f32_e32 v107, v107, v116
	v_rcp_f32_e32 v114, v114
	v_rcp_f32_e32 v115, v115
	v_exp_f32_e32 v106, v106
	v_exp_f32_e32 v107, v107
	v_add_f32_e32 v108, 1.0, v108
	v_add_f32_e32 v109, 1.0, v109
	v_mul_f32_e32 v100, v100, v116
	v_mul_f32_e32 v101, v101, v116
	v_rcp_f32_e32 v108, v108
	v_rcp_f32_e32 v109, v109
	v_add_f32_e32 v110, 1.0, v110
	v_add_f32_e32 v111, 1.0, v111
	v_exp_f32_e32 v100, v100
	v_exp_f32_e32 v101, v101
	v_mul_f32_e32 v102, v102, v116
	v_mul_f32_e32 v103, v103, v116
	v_and_b32_e32 v121, 0xffff0000, v217
	v_lshlrev_b32_e32 v122, 16, v221
	v_and_b32_e32 v123, 0xffff0000, v221
	v_rcp_f32_e32 v110, v110
	v_rcp_f32_e32 v111, v111
	v_add_f32_e32 v104, 1.0, v104
	v_add_f32_e32 v105, 1.0, v105
	v_exp_f32_e32 v102, v102
	v_exp_f32_e32 v103, v103
	v_mul_f32_e32 v96, v96, v116
	v_mul_f32_e32 v97, v97, v116
	v_pk_fma_f32 v[114:115], v[114:115], v[122:123], v[120:121]
	v_rcp_f32_e32 v104, v104
	v_rcp_f32_e32 v105, v105
	v_add_f32_e32 v106, 1.0, v106
	v_add_f32_e32 v107, 1.0, v107
	v_exp_f32_e32 v96, v96
	v_exp_f32_e32 v97, v97
	flat_store_dwordx4 v[206:207], v[112:115] offset:144
	v_rcp_f32_e32 v106, v106
	v_rcp_f32_e32 v107, v107
	v_lshlrev_b32_e32 v112, 16, v172
	v_and_b32_e32 v113, 0xffff0000, v172
	v_lshlrev_b32_e32 v114, 16, v168
	v_and_b32_e32 v115, 0xffff0000, v168
	v_pk_fma_f32 v[108:109], v[108:109], v[114:115], v[112:113]
	v_lshlrev_b32_e32 v112, 16, v173
	v_and_b32_e32 v113, 0xffff0000, v173
	v_lshlrev_b32_e32 v114, 16, v169
	v_and_b32_e32 v115, 0xffff0000, v169
	v_add_f32_e32 v100, 1.0, v100
	v_add_f32_e32 v101, 1.0, v101
	v_pk_fma_f32 v[110:111], v[110:111], v[114:115], v[112:113]
	v_lshlrev_b32_e32 v112, 16, v174
	v_and_b32_e32 v113, 0xffff0000, v174
	v_lshlrev_b32_e32 v114, 16, v170
	v_and_b32_e32 v115, 0xffff0000, v170
	v_rcp_f32_e32 v100, v100
	v_rcp_f32_e32 v101, v101
	v_add_f32_e32 v102, 1.0, v102
	v_add_f32_e32 v103, 1.0, v103
	v_pk_fma_f32 v[104:105], v[104:105], v[114:115], v[112:113]
	v_lshlrev_b32_e32 v112, 16, v175
	v_and_b32_e32 v113, 0xffff0000, v175
	v_lshlrev_b32_e32 v114, 16, v171
	v_and_b32_e32 v115, 0xffff0000, v171
	v_rcp_f32_e32 v102, v102
	v_rcp_f32_e32 v103, v103
	v_add_f32_e32 v96, 1.0, v96
	v_add_f32_e32 v97, 1.0, v97
	v_pk_fma_f32 v[106:107], v[106:107], v[114:115], v[112:113]
	v_lshl_add_u64 v[112:113], v[198:199], 2, s[2:3]
	v_rcp_f32_e32 v96, v96
	v_rcp_f32_e32 v97, v97
	flat_store_dwordx4 v[112:113], v[104:107] offset:16
	flat_store_dwordx4 v[112:113], v[108:111]
	v_mul_f32_e32 v98, v98, v116
	v_lshlrev_b32_e32 v104, 16, v164
	v_and_b32_e32 v105, 0xffff0000, v164
	v_lshlrev_b32_e32 v106, 16, v160
	v_and_b32_e32 v107, 0xffff0000, v160
	v_pk_fma_f32 v[100:101], v[100:101], v[106:107], v[104:105]
	v_lshlrev_b32_e32 v104, 16, v165
	v_and_b32_e32 v105, 0xffff0000, v165
	v_lshlrev_b32_e32 v106, 16, v161
	v_and_b32_e32 v107, 0xffff0000, v161
	v_pk_fma_f32 v[102:103], v[102:103], v[106:107], v[104:105]
	v_lshlrev_b32_e32 v104, 16, v166
	v_and_b32_e32 v105, 0xffff0000, v166
	v_lshlrev_b32_e32 v106, 16, v162
	v_and_b32_e32 v107, 0xffff0000, v162
	v_pk_fma_f32 v[96:97], v[96:97], v[106:107], v[104:105]
	v_fmamk_f32 v107, v235, 0x3a000000, v205
	v_mul_f32_e32 v108, 0x4b800000, v107
	v_cmp_gt_f32_e32 vcc, s40, v107
	flat_store_dwordx4 v[112:113], v[100:103] offset:128
	v_mul_f32_e32 v99, v99, v116
	v_cndmask_b32_e32 v107, v107, v108, vcc
	v_rsq_f32_e32 v108, v107
	v_exp_f32_e32 v98, v98
	v_exp_f32_e32 v99, v99
	v_lshlrev_b32_e32 v104, 16, v167
	v_mul_f32_e32 v100, 0x45800000, v108
	v_cndmask_b32_e32 v100, v108, v100, vcc
	v_mul_f32_e32 v100, 0xbfb8aa3b, v100
	v_mul_f32_e32 v92, v92, v100
	v_mul_f32_e32 v93, v93, v100
	v_exp_f32_e32 v92, v92
	v_exp_f32_e32 v93, v93
	v_mul_f32_e32 v94, v94, v100
	v_mul_f32_e32 v95, v95, v100
	v_exp_f32_e32 v94, v94
	v_exp_f32_e32 v95, v95
	v_mul_f32_e32 v88, v88, v100
	v_mul_f32_e32 v89, v89, v100
	v_add_f32_e32 v98, 1.0, v98
	v_add_f32_e32 v99, 1.0, v99
	v_exp_f32_e32 v88, v88
	v_exp_f32_e32 v89, v89
	v_mul_f32_e32 v90, v90, v100
	v_mul_f32_e32 v91, v91, v100
	v_rcp_f32_e32 v98, v98
	v_rcp_f32_e32 v99, v99
	v_exp_f32_e32 v90, v90
	v_exp_f32_e32 v91, v91
	v_add_f32_e32 v92, 1.0, v92
	v_add_f32_e32 v93, 1.0, v93
	v_mul_f32_e32 v84, v84, v100
	v_mul_f32_e32 v85, v85, v100
; __device__ __forceinline__ float bflo(unsigned u) { return __uint_as_float(u << 16); }
; __device__ __forceinline__ float bfhi(unsigned u) { return __uint_as_float(u & 0xffff0000u); }
;     __device__ __forceinline__ void operator()(const Acc& acc, const Unit& u, int wr, int wc, int fr, int fq) const {
;     ...
;             for (int m = 0; m < 4; ++m) {
;                 const int row = u.pm * 256 + ai * 128 + wr * 64 + m * 16 + fr;
;                 const float rs = rsqrtf(rsv[m] * (1.0f / DM) + EPS) * -1.4426950408889634f;
; #pragma unroll
;                 for (int bj = 0; bj < 2; ++bj) {
;                     const size_t off = (size_t)row * DM + colbase + 32 * bj;
;                     f32x4 h0 = hv[m][bj][0], h1 = hv[m][bj][1];
;                     const u32x4 p4 = pw[m][bj];
;                     const f32x4 a0 = acc[ai][bj][m][0], a1 = acc[ai][bj][m][1];
;                     h0.x += bflo(p4.x) * __builtin_amdgcn_rcpf(1.0f + __builtin_amdgcn_exp2f(a0.x * rs));
;                     h0.y += bfhi(p4.x) * __builtin_amdgcn_rcpf(1.0f + __builtin_amdgcn_exp2f(a0.y * rs));
;                     h0.z += bflo(p4.y) * __builtin_amdgcn_rcpf(1.0f + __builtin_amdgcn_exp2f(a0.z * rs));
;                     h0.w += bfhi(p4.y) * __builtin_amdgcn_rcpf(1.0f + __builtin_amdgcn_exp2f(a0.w * rs));
;                     h1.x += bflo(p4.z) * __builtin_amdgcn_rcpf(1.0f + __builtin_amdgcn_exp2f(a1.x * rs));
;                     h1.y += bfhi(p4.z) * __builtin_amdgcn_rcpf(1.0f + __builtin_amdgcn_exp2f(a1.y * rs));
;                     h1.z += bflo(p4.w) * __builtin_amdgcn_rcpf(1.0f + __builtin_amdgcn_exp2f(a1.z * rs));
;                     h1.w += bfhi(p4.w) * __builtin_amdgcn_rcpf(1.0f + __builtin_amdgcn_exp2f(a1.w * rs));
;                     *(f32x4*)(out + off) = h0; *(f32x4*)(out + off + 4) = h1;
	v_rcp_f32_e32 v92, v92
	v_rcp_f32_e32 v93, v93
	v_add_f32_e32 v94, 1.0, v94
	v_add_f32_e32 v95, 1.0, v95
	v_exp_f32_e32 v84, v84
	v_exp_f32_e32 v85, v85
	v_mul_f32_e32 v86, v86, v100
	v_mul_f32_e32 v87, v87, v100
	v_and_b32_e32 v105, 0xffff0000, v167
	v_lshlrev_b32_e32 v106, 16, v163
	v_and_b32_e32 v107, 0xffff0000, v163
	v_rcp_f32_e32 v94, v94
	v_rcp_f32_e32 v95, v95
	v_add_f32_e32 v88, 1.0, v88
	v_add_f32_e32 v89, 1.0, v89
	v_exp_f32_e32 v86, v86
	v_exp_f32_e32 v87, v87
	v_mul_f32_e32 v80, v80, v100
	v_mul_f32_e32 v81, v81, v100
	v_pk_fma_f32 v[98:99], v[98:99], v[106:107], v[104:105]
	v_rcp_f32_e32 v88, v88
	v_rcp_f32_e32 v89, v89
	v_add_f32_e32 v90, 1.0, v90
	v_add_f32_e32 v91, 1.0, v91
	v_exp_f32_e32 v80, v80
	v_exp_f32_e32 v81, v81
	flat_store_dwordx4 v[112:113], v[96:99] offset:144
	v_rcp_f32_e32 v90, v90
	v_rcp_f32_e32 v91, v91
	v_lshlrev_b32_e32 v96, 16, v156
	v_and_b32_e32 v97, 0xffff0000, v156
	v_lshlrev_b32_e32 v98, 16, v152
	v_and_b32_e32 v99, 0xffff0000, v152
	v_pk_fma_f32 v[92:93], v[92:93], v[98:99], v[96:97]
	v_lshlrev_b32_e32 v96, 16, v157
	v_and_b32_e32 v97, 0xffff0000, v157
	v_lshlrev_b32_e32 v98, 16, v153
	v_and_b32_e32 v99, 0xffff0000, v153
	v_add_f32_e32 v84, 1.0, v84
	v_add_f32_e32 v85, 1.0, v85
	v_pk_fma_f32 v[94:95], v[94:95], v[98:99], v[96:97]
	v_lshlrev_b32_e32 v96, 16, v158
	v_and_b32_e32 v97, 0xffff0000, v158
	v_lshlrev_b32_e32 v98, 16, v154
	v_and_b32_e32 v99, 0xffff0000, v154
	v_rcp_f32_e32 v84, v84
	v_rcp_f32_e32 v85, v85
	v_add_f32_e32 v86, 1.0, v86
	v_add_f32_e32 v87, 1.0, v87
	v_pk_fma_f32 v[88:89], v[88:89], v[98:99], v[96:97]
	v_lshlrev_b32_e32 v96, 16, v159
	v_and_b32_e32 v97, 0xffff0000, v159
	v_lshlrev_b32_e32 v98, 16, v155
	v_and_b32_e32 v99, 0xffff0000, v155
	v_rcp_f32_e32 v86, v86
	v_rcp_f32_e32 v87, v87
	v_add_f32_e32 v80, 1.0, v80
	v_add_f32_e32 v81, 1.0, v81
	v_pk_fma_f32 v[90:91], v[90:91], v[98:99], v[96:97]
	v_lshl_add_u64 v[96:97], v[196:197], 2, s[2:3]
	v_rcp_f32_e32 v80, v80
	v_rcp_f32_e32 v81, v81
	flat_store_dwordx4 v[96:97], v[88:91] offset:16
	flat_store_dwordx4 v[96:97], v[92:95]
	v_mul_f32_e32 v82, v82, v100
	v_lshlrev_b32_e32 v88, 16, v148
	v_and_b32_e32 v89, 0xffff0000, v148
	v_lshlrev_b32_e32 v90, 16, v144
	v_and_b32_e32 v91, 0xffff0000, v144
	v_pk_fma_f32 v[84:85], v[84:85], v[90:91], v[88:89]
	v_lshlrev_b32_e32 v88, 16, v149
	v_and_b32_e32 v89, 0xffff0000, v149
	v_lshlrev_b32_e32 v90, 16, v145
	v_and_b32_e32 v91, 0xffff0000, v145
	v_pk_fma_f32 v[86:87], v[86:87], v[90:91], v[88:89]
	v_lshlrev_b32_e32 v88, 16, v150
	v_and_b32_e32 v89, 0xffff0000, v150
	v_lshlrev_b32_e32 v90, 16, v146
	v_and_b32_e32 v91, 0xffff0000, v146
	v_pk_fma_f32 v[80:81], v[80:81], v[90:91], v[88:89]
	v_fmamk_f32 v91, v191, 0x3a000000, v205
	v_mul_f32_e32 v92, 0x4b800000, v91
	v_cmp_gt_f32_e32 vcc, s40, v91
	flat_store_dwordx4 v[96:97], v[84:87] offset:128
	v_mul_f32_e32 v83, v83, v100
	v_cndmask_b32_e32 v91, v91, v92, vcc
	v_rsq_f32_e32 v92, v91
	v_exp_f32_e32 v82, v82
	v_exp_f32_e32 v83, v83
	v_lshlrev_b32_e32 v88, 16, v151
	v_mul_f32_e32 v84, 0x45800000, v92
	v_cndmask_b32_e32 v84, v92, v84, vcc
	v_mul_f32_e32 v84, 0xbfb8aa3b, v84
	v_mul_f32_e32 v76, v76, v84
	v_mul_f32_e32 v77, v77, v84
	v_exp_f32_e32 v76, v76
	v_exp_f32_e32 v77, v77
	v_mul_f32_e32 v78, v78, v84
	v_mul_f32_e32 v79, v79, v84
	v_exp_f32_e32 v78, v78
	v_exp_f32_e32 v79, v79
	v_mul_f32_e32 v72, v72, v84
	v_mul_f32_e32 v73, v73, v84
	v_add_f32_e32 v82, 1.0, v82
	v_add_f32_e32 v83, 1.0, v83
	v_exp_f32_e32 v72, v72
	v_exp_f32_e32 v73, v73
	v_mul_f32_e32 v74, v74, v84
	v_mul_f32_e32 v75, v75, v84
	v_rcp_f32_e32 v82, v82
	v_rcp_f32_e32 v83, v83
	v_exp_f32_e32 v74, v74
	v_exp_f32_e32 v75, v75
	v_add_f32_e32 v76, 1.0, v76
	v_add_f32_e32 v77, 1.0, v77
	v_mul_f32_e32 v68, v68, v84
	v_mul_f32_e32 v69, v69, v84
	v_rcp_f32_e32 v76, v76
	v_rcp_f32_e32 v77, v77
	v_add_f32_e32 v78, 1.0, v78
	v_add_f32_e32 v79, 1.0, v79
	v_exp_f32_e32 v68, v68
	v_exp_f32_e32 v69, v69
	v_mul_f32_e32 v70, v70, v84
	v_mul_f32_e32 v71, v71, v84
	v_and_b32_e32 v89, 0xffff0000, v151
	v_lshlrev_b32_e32 v90, 16, v147
	v_and_b32_e32 v91, 0xffff0000, v147
	v_rcp_f32_e32 v78, v78
	v_rcp_f32_e32 v79, v79
	v_add_f32_e32 v72, 1.0, v72
	v_add_f32_e32 v73, 1.0, v73
	v_exp_f32_e32 v70, v70
	v_exp_f32_e32 v71, v71
	v_mul_f32_e32 v64, v64, v84
	v_mul_f32_e32 v65, v65, v84
	v_pk_fma_f32 v[82:83], v[82:83], v[90:91], v[88:89]
	v_rcp_f32_e32 v72, v72
	v_rcp_f32_e32 v73, v73
	v_add_f32_e32 v74, 1.0, v74
	v_add_f32_e32 v75, 1.0, v75
	v_exp_f32_e32 v64, v64
	v_exp_f32_e32 v65, v65
	v_mul_f32_e32 v66, v66, v84
	v_mul_f32_e32 v67, v67, v84
	flat_store_dwordx4 v[96:97], v[80:83] offset:144
	v_rcp_f32_e32 v74, v74
	v_rcp_f32_e32 v75, v75
	v_lshlrev_b32_e32 v80, 16, v140
	v_and_b32_e32 v81, 0xffff0000, v140
	v_lshlrev_b32_e32 v82, 16, v136
	v_and_b32_e32 v83, 0xffff0000, v136
	v_exp_f32_e32 v66, v66
	v_exp_f32_e32 v67, v67
	v_pk_fma_f32 v[76:77], v[76:77], v[82:83], v[80:81]
	v_lshlrev_b32_e32 v80, 16, v141
	v_and_b32_e32 v81, 0xffff0000, v141
	v_lshlrev_b32_e32 v82, 16, v137
	v_and_b32_e32 v83, 0xffff0000, v137
	v_add_f32_e32 v68, 1.0, v68
	v_add_f32_e32 v69, 1.0, v69
	v_pk_fma_f32 v[78:79], v[78:79], v[82:83], v[80:81]
	v_lshlrev_b32_e32 v80, 16, v142
	v_and_b32_e32 v81, 0xffff0000, v142
	v_lshlrev_b32_e32 v82, 16, v138
	v_and_b32_e32 v83, 0xffff0000, v138
	v_rcp_f32_e32 v68, v68
	v_rcp_f32_e32 v69, v69
	v_add_f32_e32 v70, 1.0, v70
	v_add_f32_e32 v71, 1.0, v71
	v_pk_fma_f32 v[72:73], v[72:73], v[82:83], v[80:81]
	v_lshlrev_b32_e32 v80, 16, v143
	v_and_b32_e32 v81, 0xffff0000, v143
	v_lshlrev_b32_e32 v82, 16, v139
	v_and_b32_e32 v83, 0xffff0000, v139
	v_rcp_f32_e32 v70, v70
	v_rcp_f32_e32 v71, v71
;     __device__ __forceinline__ void operator()(const Acc& acc, const Unit& u, int wr, int wc, int fr, int fq) const {
;     ...
;         for (int ai = 0; ai < 2; ++ai) {
;             f32x4 hv[4][2][2]; u32x4 pw[4][2]; float rsv[4];
; #pragma unroll
;             for (int m = 0; m < 4; ++m) { const int row = u.pm * 256 + ai * 128 + wr * 64 + m * 16 + fr; const size_t off = (size_t)row * DM + colbase;
;                 rsv[m] = rowss[row];
; #pragma unroll
;                 for (int bj = 0; bj < 2; ++bj) { const u32x4 hw = __builtin_nontemporal_load((const u32x4*)(hin + off + 32 * bj));
;                     hv[m][bj][0] = (f32x4){bflo(hw.x), bfhi(hw.x), bflo(hw.y), bfhi(hw.y)}; hv[m][bj][1] = (f32x4){bflo(hw.z), bfhi(hw.z), bflo(hw.w), bfhi(hw.w)};
;                     pw[m][bj] = __builtin_nontemporal_load((const u32x4*)(PP + off + 32 * bj)); } }
; #pragma unroll
;             for (int m = 0; m < 4; ++m) {
;                 const int row = u.pm * 256 + ai * 128 + wr * 64 + m * 16 + fr;
;                 const float rs = rsqrtf(rsv[m] * (1.0f / DM) + EPS) * -1.4426950408889634f;
; #pragma unroll
;                 for (int bj = 0; bj < 2; ++bj) {
;                     const size_t off = (size_t)row * DM + colbase + 32 * bj;
;                     f32x4 h0 = hv[m][bj][0], h1 = hv[m][bj][1];
;                     const u32x4 p4 = pw[m][bj];
;                     const f32x4 a0 = acc[ai][bj][m][0], a1 = acc[ai][bj][m][1];
;                     h0.x += bflo(p4.x) * __builtin_amdgcn_rcpf(1.0f + __builtin_amdgcn_exp2f(a0.x * rs));
;                     h0.y += bfhi(p4.x) * __builtin_amdgcn_rcpf(1.0f + __builtin_amdgcn_exp2f(a0.y * rs));
;                     h0.z += bflo(p4.y) * __builtin_amdgcn_rcpf(1.0f + __builtin_amdgcn_exp2f(a0.z * rs));
;                     h0.w += bfhi(p4.y) * __builtin_amdgcn_rcpf(1.0f + __builtin_amdgcn_exp2f(a0.w * rs));
;                     h1.x += bflo(p4.z) * __builtin_amdgcn_rcpf(1.0f + __builtin_amdgcn_exp2f(a1.x * rs));
;                     h1.y += bfhi(p4.z) * __builtin_amdgcn_rcpf(1.0f + __builtin_amdgcn_exp2f(a1.y * rs));
;                     h1.z += bflo(p4.w) * __builtin_amdgcn_rcpf(1.0f + __builtin_amdgcn_exp2f(a1.z * rs));
;                     h1.w += bfhi(p4.w) * __builtin_amdgcn_rcpf(1.0f + __builtin_amdgcn_exp2f(a1.w * rs));
;                     *(f32x4*)(out + off) = h0; *(f32x4*)(out + off + 4) = h1;
	v_add_f32_e32 v64, 1.0, v64
	v_add_f32_e32 v65, 1.0, v65
	v_pk_fma_f32 v[74:75], v[74:75], v[82:83], v[80:81]
	v_lshl_add_u64 v[80:81], v[194:195], 2, s[2:3]
	v_rcp_f32_e32 v64, v64
	v_rcp_f32_e32 v65, v65
	v_add_f32_e32 v66, 1.0, v66
	v_add_f32_e32 v67, 1.0, v67
	flat_store_dwordx4 v[80:81], v[72:75] offset:16
	v_rcp_f32_e32 v66, v66
	v_rcp_f32_e32 v67, v67
	v_lshlrev_b32_e32 v72, 16, v132
	v_and_b32_e32 v73, 0xffff0000, v132
	v_lshlrev_b32_e32 v74, 16, v128
	v_and_b32_e32 v75, 0xffff0000, v128
	v_pk_fma_f32 v[68:69], v[68:69], v[74:75], v[72:73]
	v_lshlrev_b32_e32 v72, 16, v133
	v_and_b32_e32 v73, 0xffff0000, v133
	v_lshlrev_b32_e32 v74, 16, v129
	v_and_b32_e32 v75, 0xffff0000, v129
	v_pk_fma_f32 v[70:71], v[70:71], v[74:75], v[72:73]
	v_lshlrev_b32_e32 v72, 16, v134
	v_and_b32_e32 v73, 0xffff0000, v134
	v_lshlrev_b32_e32 v74, 16, v130
	v_and_b32_e32 v75, 0xffff0000, v130
	v_pk_fma_f32 v[64:65], v[64:65], v[74:75], v[72:73]
	v_lshlrev_b32_e32 v72, 16, v135
	v_and_b32_e32 v73, 0xffff0000, v135
	v_lshlrev_b32_e32 v74, 16, v131
	v_and_b32_e32 v75, 0xffff0000, v131
	flat_store_dwordx4 v[80:81], v[76:79]
	v_pk_fma_f32 v[66:67], v[66:67], v[74:75], v[72:73]
	flat_store_dwordx4 v[80:81], v[68:71] offset:128
	flat_store_dwordx4 v[80:81], v[64:67] offset:144
	flat_load_dword v68, v[192:193] offset:512
	s_nop 0
	v_add_u32_e32 v64, 0x80, v190
	v_ashrrev_i32_e32 v65, 31, v64
	v_lshlrev_b64 v[64:65], 11, v[64:65]
	v_lshl_add_u64 v[136:137], v[64:65], 0, v[188:189]
	v_lshlrev_b64 v[64:65], 1, v[136:137]
	v_lshl_add_u64 v[66:67], s[6:7], 0, v[64:65]
	v_lshl_add_u64 v[64:65], s[8:9], 0, v[64:65]
	flat_load_dwordx4 v[124:127], v[66:67] nt
	flat_load_dwordx4 v[128:131], v[64:65] nt
	flat_load_dwordx4 v[132:135], v[66:67] offset:64 nt
	flat_load_dwordx4 v[112:115], v[64:65] offset:64 nt
	v_add_u32_e32 v64, 0x90, v190
	v_ashrrev_i32_e32 v65, 31, v64
	v_lshlrev_b64 v[64:65], 11, v[64:65]
	v_lshl_add_u64 v[120:121], v[64:65], 0, v[188:189]
	v_lshlrev_b64 v[64:65], 1, v[120:121]
	v_lshl_add_u64 v[66:67], s[6:7], 0, v[64:65]
	v_lshl_add_u64 v[64:65], s[8:9], 0, v[64:65]
	flat_load_dwordx4 v[108:111], v[66:67] nt
	flat_load_dwordx4 v[100:103], v[66:67] offset:64 nt
	flat_load_dwordx4 v[104:107], v[64:65] nt
	flat_load_dwordx4 v[96:99], v[64:65] offset:64 nt
	v_add_u32_e32 v64, 0xa0, v190
	v_ashrrev_i32_e32 v65, 31, v64
	v_lshlrev_b64 v[64:65], 11, v[64:65]
	v_lshl_add_u64 v[118:119], v[64:65], 0, v[188:189]
	v_lshlrev_b64 v[64:65], 1, v[118:119]
	v_lshl_add_u64 v[66:67], s[6:7], 0, v[64:65]
	v_lshl_add_u64 v[64:65], s[8:9], 0, v[64:65]
	flat_load_dwordx4 v[92:95], v[66:67] nt
	flat_load_dwordx4 v[84:87], v[66:67] offset:64 nt
	flat_load_dwordx4 v[88:91], v[64:65] nt
	flat_load_dwordx4 v[80:83], v[64:65] offset:64 nt
	flat_load_dword v123, v[192:193] offset:576
	flat_load_dword v142, v[192:193] offset:640
	flat_load_dword v122, v[192:193] offset:704
	v_add_u32_e32 v64, 0xb0, v190
	v_ashrrev_i32_e32 v65, 31, v64
	v_lshlrev_b64 v[64:65], 11, v[64:65]
	v_lshl_add_u64 v[116:117], v[64:65], 0, v[188:189]
	v_lshlrev_b64 v[64:65], 1, v[116:117]
	v_lshl_add_u64 v[66:67], s[6:7], 0, v[64:65]
	s_waitcnt vmcnt(0) lgkmcnt(0)
	v_fmamk_f32 v68, v68, 0x3a000000, v205
	v_mul_f32_e32 v69, 0x4b800000, v68
	v_cmp_gt_f32_e32 vcc, s40, v68
	v_lshlrev_b32_e32 v140, 16, v128
	s_nop 0
	v_cndmask_b32_e32 v68, v68, v69, vcc
	v_rsq_f32_e32 v70, v68
	v_lshl_add_u64 v[68:69], s[8:9], 0, v[64:65]
	v_lshlrev_b32_e32 v138, 16, v124
	v_and_b32_e32 v139, 0xffff0000, v124
	v_mul_f32_e32 v71, 0x45800000, v70
	v_cndmask_b32_e32 v70, v70, v71, vcc
	v_mul_f32_e32 v143, 0xbfb8aa3b, v70
	v_mul_f32_e32 v62, v62, v143
	v_mul_f32_e32 v63, v63, v143
	v_exp_f32_e32 v62, v62
	v_exp_f32_e32 v63, v63
	v_mul_f32_e32 v56, v56, v143
	v_mul_f32_e32 v57, v57, v143
	v_exp_f32_e32 v56, v56
	v_exp_f32_e32 v57, v57
	v_mul_f32_e32 v58, v58, v143
	v_mul_f32_e32 v59, v59, v143
	v_exp_f32_e32 v58, v58
	v_exp_f32_e32 v59, v59
	v_mul_f32_e32 v52, v52, v143
	v_mul_f32_e32 v53, v53, v143
	v_add_f32_e32 v62, 1.0, v62
	v_add_f32_e32 v63, 1.0, v63
	v_exp_f32_e32 v52, v52
	v_exp_f32_e32 v53, v53
	v_mul_f32_e32 v54, v54, v143
	v_mul_f32_e32 v55, v55, v143
	v_mul_f32_e32 v60, v60, v143
	v_mul_f32_e32 v61, v61, v143
	v_rcp_f32_e32 v62, v62
	v_rcp_f32_e32 v63, v63
	v_add_f32_e32 v56, 1.0, v56
	v_add_f32_e32 v57, 1.0, v57
	v_exp_f32_e32 v54, v54
	v_exp_f32_e32 v55, v55
	v_mul_f32_e32 v48, v48, v143
	v_mul_f32_e32 v49, v49, v143
	v_exp_f32_e32 v60, v60
	v_exp_f32_e32 v61, v61
	v_rcp_f32_e32 v56, v56
	v_rcp_f32_e32 v57, v57
	v_add_f32_e32 v58, 1.0, v58
	v_add_f32_e32 v59, 1.0, v59
	v_exp_f32_e32 v48, v48
	v_exp_f32_e32 v49, v49
	v_rcp_f32_e32 v58, v58
	v_rcp_f32_e32 v59, v59
	v_and_b32_e32 v141, 0xffff0000, v128
	v_lshlrev_b32_e32 v124, 16, v125
	v_and_b32_e32 v125, 0xffff0000, v125
	v_lshlrev_b32_e32 v128, 16, v129
	v_and_b32_e32 v129, 0xffff0000, v129
	v_add_f32_e32 v52, 1.0, v52
	v_add_f32_e32 v53, 1.0, v53
	flat_load_dwordx4 v[72:75], v[66:67] nt
	s_nop 0
	flat_load_dwordx4 v[64:67], v[66:67] offset:64 nt
	s_nop 0
	flat_load_dwordx4 v[76:79], v[68:69] nt
	s_nop 0
	flat_load_dwordx4 v[68:71], v[68:69] offset:64 nt
	v_pk_fma_f32 v[62:63], v[62:63], v[128:129], v[124:125]
	v_lshlrev_b32_e32 v124, 16, v126
	v_and_b32_e32 v125, 0xffff0000, v126
	v_lshlrev_b32_e32 v128, 16, v130
	v_and_b32_e32 v129, 0xffff0000, v130
	v_rcp_f32_e32 v52, v52
	v_rcp_f32_e32 v53, v53
	v_add_f32_e32 v54, 1.0, v54
	v_add_f32_e32 v55, 1.0, v55
	v_add_f32_e32 v60, 1.0, v60
	v_add_f32_e32 v61, 1.0, v61
	v_pk_fma_f32 v[56:57], v[56:57], v[128:129], v[124:125]
	v_lshlrev_b32_e32 v124, 16, v127
	v_and_b32_e32 v125, 0xffff0000, v127
	v_lshlrev_b32_e32 v126, 16, v131
; __device__ __forceinline__ float bflo(unsigned u) { return __uint_as_float(u << 16); }
; __device__ __forceinline__ float bfhi(unsigned u) { return __uint_as_float(u & 0xffff0000u); }
;     __device__ __forceinline__ void operator()(const Acc& acc, const Unit& u, int wr, int wc, int fr, int fq) const {
;     ...
;             for (int m = 0; m < 4; ++m) {
;                 const int row = u.pm * 256 + ai * 128 + wr * 64 + m * 16 + fr;
;                 const float rs = rsqrtf(rsv[m] * (1.0f / DM) + EPS) * -1.4426950408889634f;
; #pragma unroll
;                 for (int bj = 0; bj < 2; ++bj) {
;                     const size_t off = (size_t)row * DM + colbase + 32 * bj;
;                     f32x4 h0 = hv[m][bj][0], h1 = hv[m][bj][1];
;                     const u32x4 p4 = pw[m][bj];
;                     const f32x4 a0 = acc[ai][bj][m][0], a1 = acc[ai][bj][m][1];
;                     h0.x += bflo(p4.x) * __builtin_amdgcn_rcpf(1.0f + __builtin_amdgcn_exp2f(a0.x * rs));
;                     h0.y += bfhi(p4.x) * __builtin_amdgcn_rcpf(1.0f + __builtin_amdgcn_exp2f(a0.y * rs));
;                     h0.z += bflo(p4.y) * __builtin_amdgcn_rcpf(1.0f + __builtin_amdgcn_exp2f(a0.z * rs));
;                     h0.w += bfhi(p4.y) * __builtin_amdgcn_rcpf(1.0f + __builtin_amdgcn_exp2f(a0.w * rs));
;                     h1.x += bflo(p4.z) * __builtin_amdgcn_rcpf(1.0f + __builtin_amdgcn_exp2f(a1.x * rs));
;                     h1.y += bfhi(p4.z) * __builtin_amdgcn_rcpf(1.0f + __builtin_amdgcn_exp2f(a1.y * rs));
;                     h1.z += bflo(p4.w) * __builtin_amdgcn_rcpf(1.0f + __builtin_amdgcn_exp2f(a1.z * rs));
;                     h1.w += bfhi(p4.w) * __builtin_amdgcn_rcpf(1.0f + __builtin_amdgcn_exp2f(a1.w * rs));
;                     *(f32x4*)(out + off) = h0; *(f32x4*)(out + off + 4) = h1;
	v_and_b32_e32 v127, 0xffff0000, v131
	v_rcp_f32_e32 v54, v54
	v_rcp_f32_e32 v55, v55
	v_add_f32_e32 v48, 1.0, v48
	v_add_f32_e32 v49, 1.0, v49
	v_rcp_f32_e32 v60, v60
	v_rcp_f32_e32 v61, v61
	v_pk_fma_f32 v[58:59], v[58:59], v[126:127], v[124:125]
	v_lshl_add_u64 v[124:125], v[136:137], 2, s[2:3]
	v_rcp_f32_e32 v48, v48
	v_rcp_f32_e32 v49, v49
	flat_store_dwordx4 v[124:125], v[56:59] offset:16
	v_pk_fma_f32 v[60:61], v[60:61], v[140:141], v[138:139]
	flat_store_dwordx4 v[124:125], v[60:63]
	v_lshlrev_b32_e32 v56, 16, v132
	v_and_b32_e32 v57, 0xffff0000, v132
	v_lshlrev_b32_e32 v58, 16, v112
	v_and_b32_e32 v59, 0xffff0000, v112
	v_pk_fma_f32 v[52:53], v[52:53], v[58:59], v[56:57]
	v_lshlrev_b32_e32 v56, 16, v133
	v_and_b32_e32 v57, 0xffff0000, v133
	v_lshlrev_b32_e32 v58, 16, v113
	v_and_b32_e32 v59, 0xffff0000, v113
	v_pk_fma_f32 v[54:55], v[54:55], v[58:59], v[56:57]
	v_lshlrev_b32_e32 v56, 16, v134
	v_and_b32_e32 v57, 0xffff0000, v134
	v_lshlrev_b32_e32 v58, 16, v114
	v_and_b32_e32 v59, 0xffff0000, v114
	v_pk_fma_f32 v[48:49], v[48:49], v[58:59], v[56:57]
	v_fmamk_f32 v59, v123, 0x3a000000, v205
	v_mul_f32_e32 v60, 0x4b800000, v59
	v_cmp_gt_f32_e32 vcc, s40, v59
	flat_store_dwordx4 v[124:125], v[52:55] offset:128
	v_mul_f32_e32 v50, v50, v143
	v_cndmask_b32_e32 v59, v59, v60, vcc
	v_rsq_f32_e32 v60, v59
	v_mul_f32_e32 v51, v51, v143
	v_exp_f32_e32 v50, v50
	v_exp_f32_e32 v51, v51
	v_mul_f32_e32 v52, 0x45800000, v60
	v_cndmask_b32_e32 v52, v60, v52, vcc
	v_mul_f32_e32 v52, 0xbfb8aa3b, v52
	v_mul_f32_e32 v44, v44, v52
	v_mul_f32_e32 v45, v45, v52
	v_exp_f32_e32 v44, v44
	v_exp_f32_e32 v45, v45
	v_mul_f32_e32 v46, v46, v52
	v_mul_f32_e32 v47, v47, v52
	v_exp_f32_e32 v46, v46
	v_exp_f32_e32 v47, v47
	v_mul_f32_e32 v40, v40, v52
	v_mul_f32_e32 v41, v41, v52
	v_add_f32_e32 v50, 1.0, v50
	v_add_f32_e32 v51, 1.0, v51
	v_exp_f32_e32 v40, v40
	v_exp_f32_e32 v41, v41
	v_mul_f32_e32 v42, v42, v52
	v_mul_f32_e32 v43, v43, v52
	v_rcp_f32_e32 v50, v50
	v_rcp_f32_e32 v51, v51
	v_exp_f32_e32 v42, v42
	v_exp_f32_e32 v43, v43
	v_add_f32_e32 v44, 1.0, v44
	v_add_f32_e32 v45, 1.0, v45
	v_mul_f32_e32 v36, v36, v52
	v_mul_f32_e32 v37, v37, v52
	v_rcp_f32_e32 v44, v44
	v_rcp_f32_e32 v45, v45
	v_add_f32_e32 v46, 1.0, v46
	v_add_f32_e32 v47, 1.0, v47
	v_exp_f32_e32 v36, v36
	v_exp_f32_e32 v37, v37
	v_mul_f32_e32 v38, v38, v52
	v_mul_f32_e32 v39, v39, v52
	v_lshlrev_b32_e32 v56, 16, v135
	v_and_b32_e32 v57, 0xffff0000, v135
	v_lshlrev_b32_e32 v58, 16, v115
	v_and_b32_e32 v59, 0xffff0000, v115
	v_rcp_f32_e32 v46, v46
	v_rcp_f32_e32 v47, v47
	v_add_f32_e32 v40, 1.0, v40
	v_add_f32_e32 v41, 1.0, v41
	v_exp_f32_e32 v38, v38
	v_exp_f32_e32 v39, v39
	v_mul_f32_e32 v32, v32, v52
	v_mul_f32_e32 v33, v33, v52
	v_pk_fma_f32 v[50:51], v[50:51], v[58:59], v[56:57]
	v_rcp_f32_e32 v40, v40
	v_rcp_f32_e32 v41, v41
	v_add_f32_e32 v42, 1.0, v42
	v_add_f32_e32 v43, 1.0, v43
	v_exp_f32_e32 v32, v32
	v_exp_f32_e32 v33, v33
	flat_store_dwordx4 v[124:125], v[48:51] offset:144
	v_rcp_f32_e32 v42, v42
	v_rcp_f32_e32 v43, v43
	v_lshlrev_b32_e32 v48, 16, v108
	v_and_b32_e32 v49, 0xffff0000, v108
	v_lshlrev_b32_e32 v50, 16, v104
	v_and_b32_e32 v51, 0xffff0000, v104
	v_pk_fma_f32 v[44:45], v[44:45], v[50:51], v[48:49]
	v_lshlrev_b32_e32 v48, 16, v109
	v_and_b32_e32 v49, 0xffff0000, v109
	v_lshlrev_b32_e32 v50, 16, v105
	v_and_b32_e32 v51, 0xffff0000, v105
	v_add_f32_e32 v36, 1.0, v36
	v_add_f32_e32 v37, 1.0, v37
	v_pk_fma_f32 v[46:47], v[46:47], v[50:51], v[48:49]
	v_lshlrev_b32_e32 v48, 16, v110
	v_and_b32_e32 v49, 0xffff0000, v110
	v_lshlrev_b32_e32 v50, 16, v106
	v_and_b32_e32 v51, 0xffff0000, v106
	v_rcp_f32_e32 v36, v36
	v_rcp_f32_e32 v37, v37
	v_add_f32_e32 v38, 1.0, v38
	v_add_f32_e32 v39, 1.0, v39
	v_pk_fma_f32 v[40:41], v[40:41], v[50:51], v[48:49]
	v_lshlrev_b32_e32 v48, 16, v111
	v_and_b32_e32 v49, 0xffff0000, v111
	v_lshlrev_b32_e32 v50, 16, v107
	v_and_b32_e32 v51, 0xffff0000, v107
	v_rcp_f32_e32 v38, v38
	v_rcp_f32_e32 v39, v39
	v_add_f32_e32 v32, 1.0, v32
	v_add_f32_e32 v33, 1.0, v33
	v_pk_fma_f32 v[42:43], v[42:43], v[50:51], v[48:49]
	v_lshl_add_u64 v[48:49], v[120:121], 2, s[2:3]
	v_rcp_f32_e32 v32, v32
	v_rcp_f32_e32 v33, v33
	flat_store_dwordx4 v[48:49], v[40:43] offset:16
	flat_store_dwordx4 v[48:49], v[44:47]
	v_mul_f32_e32 v34, v34, v52
	v_lshlrev_b32_e32 v40, 16, v100
	v_and_b32_e32 v41, 0xffff0000, v100
	v_lshlrev_b32_e32 v42, 16, v96
	v_and_b32_e32 v43, 0xffff0000, v96
	v_pk_fma_f32 v[36:37], v[36:37], v[42:43], v[40:41]
	v_lshlrev_b32_e32 v40, 16, v101
	v_and_b32_e32 v41, 0xffff0000, v101
	v_lshlrev_b32_e32 v42, 16, v97
	v_and_b32_e32 v43, 0xffff0000, v97
	v_pk_fma_f32 v[38:39], v[38:39], v[42:43], v[40:41]
	v_lshlrev_b32_e32 v40, 16, v102
	v_and_b32_e32 v41, 0xffff0000, v102
	v_lshlrev_b32_e32 v42, 16, v98
	v_and_b32_e32 v43, 0xffff0000, v98
	v_pk_fma_f32 v[32:33], v[32:33], v[42:43], v[40:41]
	v_fmamk_f32 v43, v142, 0x3a000000, v205
	v_mul_f32_e32 v44, 0x4b800000, v43
	v_cmp_gt_f32_e32 vcc, s40, v43
	flat_store_dwordx4 v[48:49], v[36:39] offset:128
	v_mul_f32_e32 v35, v35, v52
	v_cndmask_b32_e32 v43, v43, v44, vcc
	v_rsq_f32_e32 v44, v43
	v_exp_f32_e32 v34, v34
	v_exp_f32_e32 v35, v35
	v_lshlrev_b32_e32 v40, 16, v103
	v_mul_f32_e32 v36, 0x45800000, v44
	v_cndmask_b32_e32 v36, v44, v36, vcc
	v_mul_f32_e32 v36, 0xbfb8aa3b, v36
	v_mul_f32_e32 v28, v28, v36
	v_mul_f32_e32 v29, v29, v36
	v_exp_f32_e32 v28, v28
	v_exp_f32_e32 v29, v29
	v_mul_f32_e32 v30, v30, v36
	v_mul_f32_e32 v31, v31, v36
	v_exp_f32_e32 v30, v30
	v_exp_f32_e32 v31, v31
	v_mul_f32_e32 v24, v24, v36
	v_mul_f32_e32 v25, v25, v36
	v_add_f32_e32 v34, 1.0, v34
	v_add_f32_e32 v35, 1.0, v35
; __device__ __forceinline__ float bflo(unsigned u) { return __uint_as_float(u << 16); }
; __device__ __forceinline__ float bfhi(unsigned u) { return __uint_as_float(u & 0xffff0000u); }
;     __device__ __forceinline__ void operator()(const Acc& acc, const Unit& u, int wr, int wc, int fr, int fq) const {
;     ...
;             for (int m = 0; m < 4; ++m) {
;                 const int row = u.pm * 256 + ai * 128 + wr * 64 + m * 16 + fr;
;                 const float rs = rsqrtf(rsv[m] * (1.0f / DM) + EPS) * -1.4426950408889634f;
; #pragma unroll
;                 for (int bj = 0; bj < 2; ++bj) {
;                     const size_t off = (size_t)row * DM + colbase + 32 * bj;
;                     f32x4 h0 = hv[m][bj][0], h1 = hv[m][bj][1];
;                     const u32x4 p4 = pw[m][bj];
;                     const f32x4 a0 = acc[ai][bj][m][0], a1 = acc[ai][bj][m][1];
;                     h0.x += bflo(p4.x) * __builtin_amdgcn_rcpf(1.0f + __builtin_amdgcn_exp2f(a0.x * rs));
;                     h0.y += bfhi(p4.x) * __builtin_amdgcn_rcpf(1.0f + __builtin_amdgcn_exp2f(a0.y * rs));
;                     h0.z += bflo(p4.y) * __builtin_amdgcn_rcpf(1.0f + __builtin_amdgcn_exp2f(a0.z * rs));
;                     h0.w += bfhi(p4.y) * __builtin_amdgcn_rcpf(1.0f + __builtin_amdgcn_exp2f(a0.w * rs));
;                     h1.x += bflo(p4.z) * __builtin_amdgcn_rcpf(1.0f + __builtin_amdgcn_exp2f(a1.x * rs));
;                     h1.y += bfhi(p4.z) * __builtin_amdgcn_rcpf(1.0f + __builtin_amdgcn_exp2f(a1.y * rs));
;                     h1.z += bflo(p4.w) * __builtin_amdgcn_rcpf(1.0f + __builtin_amdgcn_exp2f(a1.z * rs));
;                     h1.w += bfhi(p4.w) * __builtin_amdgcn_rcpf(1.0f + __builtin_amdgcn_exp2f(a1.w * rs));
;                     *(f32x4*)(out + off) = h0; *(f32x4*)(out + off + 4) = h1;
	v_exp_f32_e32 v24, v24
	v_exp_f32_e32 v25, v25
	v_mul_f32_e32 v26, v26, v36
	v_mul_f32_e32 v27, v27, v36
	v_rcp_f32_e32 v34, v34
	v_rcp_f32_e32 v35, v35
	v_exp_f32_e32 v26, v26
	v_exp_f32_e32 v27, v27
	v_add_f32_e32 v28, 1.0, v28
	v_add_f32_e32 v29, 1.0, v29
	v_mul_f32_e32 v20, v20, v36
	v_mul_f32_e32 v21, v21, v36
	v_rcp_f32_e32 v28, v28
	v_rcp_f32_e32 v29, v29
	v_add_f32_e32 v30, 1.0, v30
	v_add_f32_e32 v31, 1.0, v31
	v_exp_f32_e32 v20, v20
	v_exp_f32_e32 v21, v21
	v_mul_f32_e32 v22, v22, v36
	v_mul_f32_e32 v23, v23, v36
	v_and_b32_e32 v41, 0xffff0000, v103
	v_lshlrev_b32_e32 v42, 16, v99
	v_and_b32_e32 v43, 0xffff0000, v99
	v_rcp_f32_e32 v30, v30
	v_rcp_f32_e32 v31, v31
	v_add_f32_e32 v24, 1.0, v24
	v_add_f32_e32 v25, 1.0, v25
	v_exp_f32_e32 v22, v22
	v_exp_f32_e32 v23, v23
	v_mul_f32_e32 v16, v16, v36
	v_mul_f32_e32 v17, v17, v36
	v_pk_fma_f32 v[34:35], v[34:35], v[42:43], v[40:41]
	v_rcp_f32_e32 v24, v24
	v_rcp_f32_e32 v25, v25
	v_add_f32_e32 v26, 1.0, v26
	v_add_f32_e32 v27, 1.0, v27
	v_exp_f32_e32 v16, v16
	v_exp_f32_e32 v17, v17
	flat_store_dwordx4 v[48:49], v[32:35] offset:144
	v_rcp_f32_e32 v26, v26
	v_rcp_f32_e32 v27, v27
	v_lshlrev_b32_e32 v32, 16, v92
	v_and_b32_e32 v33, 0xffff0000, v92
	v_lshlrev_b32_e32 v34, 16, v88
	v_and_b32_e32 v35, 0xffff0000, v88
	v_pk_fma_f32 v[28:29], v[28:29], v[34:35], v[32:33]
	v_lshlrev_b32_e32 v32, 16, v93
	v_and_b32_e32 v33, 0xffff0000, v93
	v_lshlrev_b32_e32 v34, 16, v89
	v_and_b32_e32 v35, 0xffff0000, v89
	v_add_f32_e32 v20, 1.0, v20
	v_add_f32_e32 v21, 1.0, v21
	v_pk_fma_f32 v[30:31], v[30:31], v[34:35], v[32:33]
	v_lshlrev_b32_e32 v32, 16, v94
	v_and_b32_e32 v33, 0xffff0000, v94
	v_lshlrev_b32_e32 v34, 16, v90
	v_and_b32_e32 v35, 0xffff0000, v90
	v_rcp_f32_e32 v20, v20
	v_rcp_f32_e32 v21, v21
	v_add_f32_e32 v22, 1.0, v22
	v_add_f32_e32 v23, 1.0, v23
	v_pk_fma_f32 v[24:25], v[24:25], v[34:35], v[32:33]
	v_lshlrev_b32_e32 v32, 16, v95
	v_and_b32_e32 v33, 0xffff0000, v95
	v_lshlrev_b32_e32 v34, 16, v91
	v_and_b32_e32 v35, 0xffff0000, v91
	v_rcp_f32_e32 v22, v22
	v_rcp_f32_e32 v23, v23
	v_add_f32_e32 v16, 1.0, v16
	v_add_f32_e32 v17, 1.0, v17
	v_pk_fma_f32 v[26:27], v[26:27], v[34:35], v[32:33]
	v_lshl_add_u64 v[32:33], v[118:119], 2, s[2:3]
	v_rcp_f32_e32 v16, v16
	v_rcp_f32_e32 v17, v17
	flat_store_dwordx4 v[32:33], v[24:27] offset:16
	flat_store_dwordx4 v[32:33], v[28:31]
	v_mul_f32_e32 v18, v18, v36
	v_lshlrev_b32_e32 v24, 16, v84
	v_and_b32_e32 v25, 0xffff0000, v84
	v_lshlrev_b32_e32 v26, 16, v80
	v_and_b32_e32 v27, 0xffff0000, v80
	v_pk_fma_f32 v[20:21], v[20:21], v[26:27], v[24:25]
	v_lshlrev_b32_e32 v24, 16, v85
	v_and_b32_e32 v25, 0xffff0000, v85
	v_lshlrev_b32_e32 v26, 16, v81
	v_and_b32_e32 v27, 0xffff0000, v81
	v_pk_fma_f32 v[22:23], v[22:23], v[26:27], v[24:25]
	v_lshlrev_b32_e32 v24, 16, v86
	v_and_b32_e32 v25, 0xffff0000, v86
	v_lshlrev_b32_e32 v26, 16, v82
	v_and_b32_e32 v27, 0xffff0000, v82
	v_pk_fma_f32 v[16:17], v[16:17], v[26:27], v[24:25]
	v_fmamk_f32 v27, v122, 0x3a000000, v205
	v_mul_f32_e32 v28, 0x4b800000, v27
	v_cmp_gt_f32_e32 vcc, s40, v27
	flat_store_dwordx4 v[32:33], v[20:23] offset:128
	v_mul_f32_e32 v19, v19, v36
	v_cndmask_b32_e32 v27, v27, v28, vcc
	v_rsq_f32_e32 v28, v27
	v_exp_f32_e32 v18, v18
	v_exp_f32_e32 v19, v19
	v_lshlrev_b32_e32 v24, 16, v87
	v_mul_f32_e32 v20, 0x45800000, v28
	v_cndmask_b32_e32 v20, v28, v20, vcc
	v_mul_f32_e32 v20, 0xbfb8aa3b, v20
	v_mul_f32_e32 v12, v12, v20
	v_mul_f32_e32 v13, v13, v20
	v_exp_f32_e32 v12, v12
	v_exp_f32_e32 v13, v13
	v_mul_f32_e32 v14, v14, v20
	v_mul_f32_e32 v15, v15, v20
	v_exp_f32_e32 v14, v14
	v_exp_f32_e32 v15, v15
	v_mul_f32_e32 v8, v8, v20
	v_mul_f32_e32 v9, v9, v20
	v_add_f32_e32 v18, 1.0, v18
	v_add_f32_e32 v19, 1.0, v19
	v_exp_f32_e32 v8, v8
	v_exp_f32_e32 v9, v9
	v_mul_f32_e32 v10, v10, v20
	v_mul_f32_e32 v11, v11, v20
	v_rcp_f32_e32 v18, v18
	v_rcp_f32_e32 v19, v19
	v_exp_f32_e32 v10, v10
	v_exp_f32_e32 v11, v11
	v_add_f32_e32 v12, 1.0, v12
	v_add_f32_e32 v13, 1.0, v13
	v_mul_f32_e32 v4, v4, v20
	v_mul_f32_e32 v5, v5, v20
	v_rcp_f32_e32 v12, v12
	v_rcp_f32_e32 v13, v13
	v_add_f32_e32 v14, 1.0, v14
	v_add_f32_e32 v15, 1.0, v15
	v_exp_f32_e32 v4, v4
	v_exp_f32_e32 v5, v5
	v_mul_f32_e32 v6, v6, v20
	v_mul_f32_e32 v7, v7, v20
	v_and_b32_e32 v25, 0xffff0000, v87
	v_lshlrev_b32_e32 v26, 16, v83
	v_and_b32_e32 v27, 0xffff0000, v83
	v_rcp_f32_e32 v14, v14
	v_rcp_f32_e32 v15, v15
	v_add_f32_e32 v8, 1.0, v8
	v_add_f32_e32 v9, 1.0, v9
	v_exp_f32_e32 v6, v6
	v_exp_f32_e32 v7, v7
	v_mul_f32_e32 v0, v0, v20
	v_mul_f32_e32 v1, v1, v20
	v_pk_fma_f32 v[18:19], v[18:19], v[26:27], v[24:25]
	v_rcp_f32_e32 v8, v8
	v_rcp_f32_e32 v9, v9
	v_add_f32_e32 v10, 1.0, v10
	v_add_f32_e32 v11, 1.0, v11
	v_exp_f32_e32 v0, v0
	v_exp_f32_e32 v1, v1
	v_mul_f32_e32 v2, v2, v20
	v_mul_f32_e32 v3, v3, v20
	flat_store_dwordx4 v[32:33], v[16:19] offset:144
	v_rcp_f32_e32 v10, v10
	v_rcp_f32_e32 v11, v11
	s_waitcnt vmcnt(0) lgkmcnt(0)
; __device__ __forceinline__ float bflo(unsigned u) { return __uint_as_float(u << 16); }
; __device__ __forceinline__ float bfhi(unsigned u) { return __uint_as_float(u & 0xffff0000u); }
;     __device__ __forceinline__ void operator()(const Acc& acc, const Unit& u, int wr, int wc, int fr, int fq) const {
;     ...
;                     h0.x += bflo(p4.x) * __builtin_amdgcn_rcpf(1.0f + __builtin_amdgcn_exp2f(a0.x * rs));
;                     h0.y += bfhi(p4.x) * __builtin_amdgcn_rcpf(1.0f + __builtin_amdgcn_exp2f(a0.y * rs));
;                     h0.z += bflo(p4.y) * __builtin_amdgcn_rcpf(1.0f + __builtin_amdgcn_exp2f(a0.z * rs));
;                     h0.w += bfhi(p4.y) * __builtin_amdgcn_rcpf(1.0f + __builtin_amdgcn_exp2f(a0.w * rs));
;                     h1.x += bflo(p4.z) * __builtin_amdgcn_rcpf(1.0f + __builtin_amdgcn_exp2f(a1.x * rs));
;                     h1.y += bfhi(p4.z) * __builtin_amdgcn_rcpf(1.0f + __builtin_amdgcn_exp2f(a1.y * rs));
;                     h1.z += bflo(p4.w) * __builtin_amdgcn_rcpf(1.0f + __builtin_amdgcn_exp2f(a1.z * rs));
;                     h1.w += bfhi(p4.w) * __builtin_amdgcn_rcpf(1.0f + __builtin_amdgcn_exp2f(a1.w * rs));
;                     *(f32x4*)(out + off) = h0; *(f32x4*)(out + off + 4) = h1;
	v_lshlrev_b32_e32 v16, 16, v72
	v_and_b32_e32 v17, 0xffff0000, v72
	v_lshlrev_b32_e32 v18, 16, v76
	v_and_b32_e32 v19, 0xffff0000, v76
	v_exp_f32_e32 v2, v2
	v_exp_f32_e32 v3, v3
	v_pk_fma_f32 v[12:13], v[12:13], v[18:19], v[16:17]
	v_lshlrev_b32_e32 v16, 16, v73
	v_and_b32_e32 v17, 0xffff0000, v73
	v_lshlrev_b32_e32 v18, 16, v77
	v_and_b32_e32 v19, 0xffff0000, v77
	v_add_f32_e32 v4, 1.0, v4
	v_add_f32_e32 v5, 1.0, v5
	v_pk_fma_f32 v[14:15], v[14:15], v[18:19], v[16:17]
	v_lshlrev_b32_e32 v16, 16, v74
	v_and_b32_e32 v17, 0xffff0000, v74
	v_lshlrev_b32_e32 v18, 16, v78
	v_and_b32_e32 v19, 0xffff0000, v78
	v_rcp_f32_e32 v4, v4
	v_rcp_f32_e32 v5, v5
	v_add_f32_e32 v6, 1.0, v6
	v_add_f32_e32 v7, 1.0, v7
	v_pk_fma_f32 v[8:9], v[8:9], v[18:19], v[16:17]
	v_lshlrev_b32_e32 v16, 16, v75
	v_and_b32_e32 v17, 0xffff0000, v75
	v_lshlrev_b32_e32 v18, 16, v79
	v_and_b32_e32 v19, 0xffff0000, v79
	v_rcp_f32_e32 v6, v6
	v_rcp_f32_e32 v7, v7
	v_add_f32_e32 v0, 1.0, v0
	v_add_f32_e32 v1, 1.0, v1
	v_pk_fma_f32 v[10:11], v[10:11], v[18:19], v[16:17]
	v_lshl_add_u64 v[16:17], v[116:117], 2, s[2:3]
	v_rcp_f32_e32 v0, v0
	v_rcp_f32_e32 v1, v1
	v_add_f32_e32 v2, 1.0, v2
	v_add_f32_e32 v3, 1.0, v3
	flat_store_dwordx4 v[16:17], v[8:11] offset:16
	v_rcp_f32_e32 v2, v2
	v_rcp_f32_e32 v3, v3
	v_lshlrev_b32_e32 v8, 16, v64
	v_and_b32_e32 v9, 0xffff0000, v64
	v_lshlrev_b32_e32 v10, 16, v68
	v_and_b32_e32 v11, 0xffff0000, v68
	v_pk_fma_f32 v[4:5], v[4:5], v[10:11], v[8:9]
	v_lshlrev_b32_e32 v8, 16, v65
	v_and_b32_e32 v9, 0xffff0000, v65
	v_lshlrev_b32_e32 v10, 16, v69
	v_and_b32_e32 v11, 0xffff0000, v69
	v_pk_fma_f32 v[6:7], v[6:7], v[10:11], v[8:9]
	v_lshlrev_b32_e32 v8, 16, v66
	v_and_b32_e32 v9, 0xffff0000, v66
	v_lshlrev_b32_e32 v10, 16, v70
	v_and_b32_e32 v11, 0xffff0000, v70
	v_pk_fma_f32 v[0:1], v[0:1], v[10:11], v[8:9]
	v_lshlrev_b32_e32 v8, 16, v67
	v_and_b32_e32 v9, 0xffff0000, v67
	v_lshlrev_b32_e32 v10, 16, v71
	v_and_b32_e32 v11, 0xffff0000, v71
	s_andn2_b64 vcc, exec, s[4:5]
	s_mov_b64 s[4:5], -1
	flat_store_dwordx4 v[16:17], v[12:15]
	v_pk_fma_f32 v[2:3], v[2:3], v[10:11], v[8:9]
	flat_store_dwordx4 v[16:17], v[4:7] offset:128
	flat_store_dwordx4 v[16:17], v[0:3] offset:144
	s_cbranch_vccnz .LBB0_803
	s_and_b64 vcc, exec, s[0:1]
	s_cbranch_vccnz .LBB0_802
	s_barrier
	s_branch .LBB0_802
